# v14: EpiRes GEMMs: last partial round split into M-half work units (half MFMA blocks skipped, stores of other half masked)
# speedup vs baseline: 1.0000x; 1.0000x over previous
; #define PG8_STAGE(bufoff, gbase, voff) do { _Pragma("unroll") for (int _i = 0; _i < 2; ++_i) \
;         __builtin_amdgcn_global_load_lds((const unsigned*)((const char*)(gbase) + (voff)[_i]), (PG8_LAS unsigned*)(lds + (bufoff) + ldsw + _i * 8192), 16, 0, 0); } while (0)
; #define PG8_WAIT_V(n) asm volatile("s_waitcnt vmcnt(" #n ")" ::: "memory")
; #define PG8_BAR __builtin_amdgcn_s_barrier()
; template <class Epi, class Sched, bool ALIGN_EPI = false, bool SP2 = false>
; __device__ __forceinline__ void gemm_phase(PG8_LAS unsigned char* lds, const Gemm g, const Sched& S, const Epi& E, int tid_in) {
;     ...
;     const char* cA = (const char*)g.A + (size_t)cur.pm * tstepA + a_unit_off(g, cur.pn); const char* cB = (const char*)g.Bt + (size_t)cur.pn * tstepB;
;     S.a_ready(cur);
;     if constexpr (SP2) {
;         PG8_STAGE(PG8_SB(0, 0), cB, voffB); PG8_STAGE(PG8_SB(0, 1), cB + hstep, voffB); PG8_STAGE(PG8_SA(0, 0), cA, voffA); PG8_STAGE(PG8_SA(0, 1), cA + hstepA, voffA);
;         if (wr == 1) PG8_BAR;
;         PG8_WAIT_V(2); PG8_BAR;
;         PG8_STAGE(PG8_SB(1, 0), cB + kstep, voffB); PG8_STAGE(PG8_SA(1, 0), cA + kstep, voffA); PG8_STAGE(PG8_SB(1, 1), cB + hstep + kstep, voffB);
;         PG8_WAIT_V(6); PG8_BAR;
;     } else {
;         PG8_STAGE(PG8_SB(0, 0), cB, voffB); PG8_STAGE(PG8_SA(0, 0), cA, voffA); PG8_STAGE(PG8_SB(0, 1), cB + hstep, voffB); PG8_STAGE(PG8_SA(0, 1), cA + hstepA, voffA);
;         if (wr == 1) PG8_BAR;
;         PG8_WAIT_V(4); PG8_BAR;
;         PG8_STAGE(PG8_SB(1, 0), cB + kstep, voffB); PG8_STAGE(PG8_SA(1, 0), cA + kstep, voffA); PG8_STAGE(PG8_SB(1, 1), cB + hstep + kstep, voffB);
;         PG8_WAIT_V(6); PG8_BAR;
;     }
.LBB0_527:
	s_add_i32 m0, s62, 0x18000
	v_lshl_add_u64 v[2:3], v[2:3], 0, s[28:29]
	s_waitcnt vmcnt(2)
	s_barrier
	global_load_lds_dwordx4 v[2:3], off
	v_lshl_add_u64 v[2:3], v[4:5], 0, s[28:29]
	s_add_i32 m0, s62, 0x1a000
	s_add_i32 s66, s62, 0x8000
	global_load_lds_dwordx4 v[2:3], off
	v_lshl_add_u64 v[2:3], v[10:11], 0, s[28:29]
	s_mov_b32 m0, s66
	s_add_i32 s67, s62, 0xa000
	global_load_lds_dwordx4 v[2:3], off
	v_lshl_add_u64 v[2:3], v[12:13], 0, s[28:29]
	s_mov_b32 m0, s67
	s_and_b32 s68, s12, 3
	global_load_lds_dwordx4 v[2:3], off
	s_add_i32 m0, s62, 0x1c000
	v_lshl_add_u64 v[2:3], v[6:7], 0, s[28:29]
	global_load_lds_dwordx4 v[2:3], off
	v_lshl_add_u64 v[2:3], v[8:9], 0, s[28:29]
	s_add_i32 m0, s62, 0x1e000
	s_lshr_b32 s12, s37, 26
	global_load_lds_dwordx4 v[2:3], off
	v_bfe_u32 v2, v203, 4, 2
	v_and_b32_e32 v3, 15, v203
	v_lshlrev_b32_e32 v5, 4, v2
	s_add_i32 s12, s36, s12
	v_lshl_or_b32 v150, s13, 6, v3
	v_lshl_or_b32 v3, v3, 6, v5
	v_lshlrev_b32_e32 v5, 2, v203
	s_ashr_i32 s69, s12, 6
	s_lshl_b32 s12, s13, 13
	v_and_b32_e32 v5, 32, v5
	v_bitop3_b32 v6, v3, s12, v5 bitop3:0xde
	s_lshl_b32 s12, s68, 12
	v_lshlrev_b32_e32 v4, 3, v2
	s_cmp_gt_i32 s36, 63
	v_cmp_eq_u32_e64 s[36:37], 0, v2
	v_add_u32_e32 v2, v16, v14
	v_bitop3_b32 v151, s12, v3, v5 bitop3:0xf6
	s_cselect_b64 s[46:47], -1, 0
	s_add_i32 s70, s69, -2
	v_add_lshl_u32 v2, v2, v15, 1
	v_mov_b32_e32 v3, v1
	s_waitcnt vmcnt(6)
	s_cmpk_lt_u32 s15, 0x100
	v_lshl_add_u64 v[136:137], s[22:23], 0, v[2:3]
	v_add_u32_e32 v2, v19, v17
	s_cselect_b64 s[48:49], -1, 0
	s_lshr_b32 s72, s60, 1
	v_add_lshl_u32 v2, v2, v18, 1
	v_lshl_or_b32 v152, s68, 5, v4
	s_mov_b32 s71, 0
	s_mov_b32 s21, s25
	s_and_b32 s73, s20, 4
	s_add_i32 s74, s72, 1
	s_or_b32 s75, s61, 0x80
	s_or_b32 s76, s61, 0x90
	s_or_b32 s77, s61, 0xa0
	s_or_b32 s78, s61, 0xb0
	v_lshl_add_u64 v[138:139], s[22:23], 0, v[2:3]
	v_add_u32_e32 v153, 0, v6
	s_movk_i32 s81, 0x4040
	s_barrier
	s_mov_b32 s98, 0
	s_mov_b32 s100, 0
	s_branch .LBB0_530

;     __host__ __device__ bool next(int i, Unit& u) const {
;         const long L = (long)i * G + c; if (L >= nwg) return false;
;         int wgid = (int)L; { const int q = nwg / NXCD, r = nwg % NXCD, xcd = wgid % NXCD, off = wgid / NXCD; wgid = (xcd < r ? xcd * (q + 1) : r * (q + 1) + (xcd - r) * q) + off; }
;         const int nig = WGM * nN, gid = wgid / nig, fm = gid * WGM, gsz = (nM - fm) < WGM ? (nM - fm) : WGM;
;         u.pm = fm + ((wgid % nig) % gsz); u.pn = (wgid % nig) / gsz; return true;
; template <class Epi, class Sched, bool ALIGN_EPI = false, bool SP2 = false>
; __device__ __forceinline__ void gemm_phase(PG8_LAS unsigned char* lds, const Gemm g, const Sched& S, const Epi& E, int tid_in) {
;     ...
;         cur = nxt; cA = nA; cB = nB; ++ui;
.LBB0_529:
	s_mov_b32 s98, s100
	s_andn2_b64 vcc, exec, s[12:13]
	s_mov_b32 s24, s79
	s_mov_b32 s56, s80
	s_mov_b64 s[54:55], s[50:51]
	s_mov_b64 s[52:53], s[40:41]
	s_cbranch_vccz .LBB0_661
.LBB0_530:
	s_add_i32 s71, s71, 1
	s_mul_i32 s12, s71, s87
	s_mul_hi_u32 s13, s71, s94
	s_add_i32 s13, s13, s12
	s_mul_i32 s12, s71, s94
	s_add_u32 s12, s12, s96
	s_addc_u32 s13, s13, s97
	s_mov_b32 s100, 0
	s_cmp_lg_u32 s94, 0x100
	s_cbranch_scc1 .Lhalf_sched_done
	s_lshr_b32 s99, s20, 8
	s_cmp_lg_u32 s71, s99
	s_cbranch_scc1 .Lhalf_sched_done
	s_and_b32 s101, s20, 0xff
	s_lshl_b32 s101, s101, 1
	s_mov_b32 s12, s20
	s_mov_b32 s13, 0
	s_cmp_ge_u32 s96, s101
	s_cbranch_scc1 .Lhalf_sched_done
	s_lshr_b32 s12, s96, 1
	s_lshl_b32 s101, s99, 8
	s_add_i32 s12, s12, s101
	s_and_b32 s100, s96, 1
	s_add_i32 s100, s100, 1
.Lhalf_sched_done:
	s_waitcnt lgkmcnt(0)
	v_mov_b64_e32 v[2:3], s[20:21]
	v_cmp_ge_i64_e32 vcc, s[12:13], v[2:3]
	v_cmp_lt_i64_e64 s[40:41], s[12:13], v[2:3]
	s_cbranch_vccnz .LBB0_536
	s_ashr_i32 s13, s12, 31
	s_lshr_b32 s13, s13, 29
	s_add_i32 s15, s12, s13
	s_and_b32 s13, s15, -8
	s_sub_i32 s38, s12, s13
	s_cmp_ge_i32 s38, s73
	s_mov_b64 s[12:13], -1
	s_cbranch_scc0 .LBB0_533
	s_sub_i32 s12, s38, s73
	s_mul_i32 s12, s12, s72
	s_mul_i32 s13, s74, s73
	s_add_i32 s39, s12, s13
	s_mov_b64 s[12:13], 0

; #define PG8_STAGE(bufoff, gbase, voff) do { _Pragma("unroll") for (int _i = 0; _i < 2; ++_i) \
;         __builtin_amdgcn_global_load_lds((const unsigned*)((const char*)(gbase) + (voff)[_i]), (PG8_LAS unsigned*)(lds + (bufoff) + ldsw + _i * 8192), 16, 0, 0); } while (0)
; #define PG8_LDA(dst, b, h) do { _Pragma("unroll") for (int m = 0; m < 4; ++m) _Pragma("unroll") for (int k = 0; k < 2; ++k) dst[m][k] = *(const PG8_LAS bf16x8*)(lds + PG8_SA(b, h) + aoff + m * 2048 + k * 1024); } while (0)
; #define PG8_LDB(dst, b, h) do { _Pragma("unroll") for (int n = 0; n < 2; ++n) _Pragma("unroll") for (int k = 0; k < 2; ++k) dst[n][k] = *(const PG8_LAS bf16x8*)(lds + PG8_SB(b, h) + boff + n * 2048 + k * 1024); } while (0)
; #define PG8_MMA(ai, bj, At, Bt) do { __builtin_amdgcn_s_setprio(1); _Pragma("unroll") for (int m = 0; m < 4; ++m) _Pragma("unroll") for (int n = 0; n < 2; ++n) _Pragma("unroll") for (int k = 0; k < 2; ++k) \
;         acc[ai][bj][m][n] = __builtin_amdgcn_mfma_f32_16x16x32_bf16(Bt[n][k], At[m][k], acc[ai][bj][m][n], 0, 0, 0); __builtin_amdgcn_s_setprio(0); } while (0)
; #define PG8_WAIT_V(n) asm volatile("s_waitcnt vmcnt(" #n ")" ::: "memory")
; #define PG8_WAIT_L(n) asm volatile("s_waitcnt lgkmcnt(" #n ")" ::: "memory")
; #define PG8_BAR __builtin_amdgcn_s_barrier()
; #define PG8_SCHED __builtin_amdgcn_sched_barrier(0)
; template <class Epi, class Sched, bool ALIGN_EPI = false, bool SP2 = false>
; __device__ __forceinline__ void gemm_phase(PG8_LAS unsigned char* lds, const Gemm g, const Sched& S, const Epi& E, int tid_in) {
;     ...
;             PG8_LDB(B0, 0, 0); PG8_LDB(B1, 0, 1); PG8_SCHED; PG8_LDA(At, 0, 0); PG8_STAGE(PG8_SA(1, 1), a1 + hstepA, voffA);
;             PG8_WAIT_V(8); PG8_WAIT_L(0); PG8_BAR; PG8_MMA(0, 0, At, B0); PG8_MMA(0, 1, At, B1); PG8_BAR; PG8_SCHED;
;             PG8_LDA(At, 0, 1); PG8_STAGE(PG8_SB(0, 0), b2, voffB); PG8_STAGE(PG8_SB(0, 1), b2 + hstep, voffB); PG8_STAGE(PG8_SA(0, 0), a2, voffA);
;             PG8_WAIT_V(8); PG8_WAIT_L(0); PG8_BAR; PG8_MMA(1, 0, At, B0); PG8_MMA(1, 1, At, B1); PG8_BAR; PG8_SCHED;
.LBB0_542:
	s_add_i32 s57, s15, 2
	s_add_u32 s54, s52, 0x80
	s_addc_u32 s55, s53, 0
	s_add_i32 s81, 0, 0x10000
	s_cmp_eq_u32 s70, s15
	s_cselect_b32 s55, s41, s55
	s_cselect_b32 s54, s40, s54
	v_add_u32_e32 v148, s81, v151
	s_cselect_b32 s59, s51, s13
	s_cselect_b32 s58, s50, s12
	s_add_i32 s15, 0, 0x14000
	ds_read_b128 v[140:143], v148
	ds_read_b128 v[144:147], v148 offset:1024
	ds_read_b128 v[154:157], v148 offset:2048
	ds_read_b128 v[158:161], v148 offset:3072
	v_add_u32_e32 v148, s15, v151
	ds_read_b128 v[162:165], v148
	ds_read_b128 v[166:169], v148 offset:1024
	ds_read_b128 v[170:173], v148 offset:2048
	ds_read_b128 v[174:177], v148 offset:3072
	v_lshl_add_u64 v[148:149], s[52:53], 0, v[136:137]
	s_add_i32 m0, s62, 0xc000
	s_cmp_eq_u32 s98, 2
	s_cbranch_scc1 .Lhalf_r0
	ds_read_b128 v[178:181], v153
	ds_read_b128 v[182:185], v153 offset:1024
	ds_read_b128 v[186:189], v153 offset:2048
	ds_read_b128 v[190:193], v153 offset:3072
	ds_read_b128 v[204:207], v153 offset:4096
	ds_read_b128 v[208:211], v153 offset:5120
	ds_read_b128 v[212:215], v153 offset:6144
	ds_read_b128 v[216:219], v153 offset:7168
.Lhalf_r0:
	global_load_lds_dwordx4 v[148:149], off
	v_lshl_add_u64 v[148:149], s[52:53], 0, v[138:139]
	s_add_i32 m0, s62, 0xe000
	s_nop 0
	global_load_lds_dwordx4 v[148:149], off
	s_waitcnt vmcnt(8)
	s_waitcnt lgkmcnt(0)
	s_barrier
	s_setprio 1
	s_waitcnt lgkmcnt(0)
	s_cmp_eq_u32 s98, 2
	s_cbranch_scc1 .Lhalf_m0
	v_mfma_f32_16x16x32_bf16 v[126:129], v[140:143], v[178:181], v[126:129]
	v_mfma_f32_16x16x32_bf16 v[122:125], v[154:157], v[178:181], v[122:125]
	v_mfma_f32_16x16x32_bf16 v[110:113], v[140:143], v[186:189], v[110:113]
	v_mfma_f32_16x16x32_bf16 v[106:109], v[154:157], v[186:189], v[106:109]
	v_mfma_f32_16x16x32_bf16 v[94:97], v[140:143], v[204:207], v[94:97]
	v_mfma_f32_16x16x32_bf16 v[90:93], v[154:157], v[204:207], v[90:93]
	v_mfma_f32_16x16x32_bf16 v[78:81], v[140:143], v[212:215], v[78:81]
	v_mfma_f32_16x16x32_bf16 v[74:77], v[154:157], v[212:215], v[74:77]
	v_mfma_f32_16x16x32_bf16 v[126:129], v[144:147], v[182:185], v[126:129]
	v_mfma_f32_16x16x32_bf16 v[122:125], v[158:161], v[182:185], v[122:125]
	v_mfma_f32_16x16x32_bf16 v[110:113], v[144:147], v[190:193], v[110:113]
	v_mfma_f32_16x16x32_bf16 v[106:109], v[158:161], v[190:193], v[106:109]
	v_mfma_f32_16x16x32_bf16 v[94:97], v[144:147], v[208:211], v[94:97]
	v_mfma_f32_16x16x32_bf16 v[90:93], v[158:161], v[208:211], v[90:93]
	v_mfma_f32_16x16x32_bf16 v[78:81], v[144:147], v[216:219], v[78:81]
	v_mfma_f32_16x16x32_bf16 v[74:77], v[158:161], v[216:219], v[74:77]
	s_setprio 0
	s_setprio 1
	v_mfma_f32_16x16x32_bf16 v[118:121], v[162:165], v[178:181], v[118:121]
	v_mfma_f32_16x16x32_bf16 v[114:117], v[170:173], v[178:181], v[114:117]
	v_mfma_f32_16x16x32_bf16 v[102:105], v[162:165], v[186:189], v[102:105]
	v_mfma_f32_16x16x32_bf16 v[98:101], v[170:173], v[186:189], v[98:101]
	v_mfma_f32_16x16x32_bf16 v[86:89], v[162:165], v[204:207], v[86:89]
	v_mfma_f32_16x16x32_bf16 v[82:85], v[170:173], v[204:207], v[82:85]
	v_mfma_f32_16x16x32_bf16 v[70:73], v[162:165], v[212:215], v[70:73]
	v_mfma_f32_16x16x32_bf16 v[66:69], v[170:173], v[212:215], v[66:69]
	v_mfma_f32_16x16x32_bf16 v[118:121], v[166:169], v[182:185], v[118:121]
	v_mfma_f32_16x16x32_bf16 v[114:117], v[174:177], v[182:185], v[114:117]
	v_mfma_f32_16x16x32_bf16 v[102:105], v[166:169], v[190:193], v[102:105]
	v_mfma_f32_16x16x32_bf16 v[98:101], v[174:177], v[190:193], v[98:101]
	v_mfma_f32_16x16x32_bf16 v[86:89], v[166:169], v[208:211], v[86:89]
	v_mfma_f32_16x16x32_bf16 v[82:85], v[174:177], v[208:211], v[82:85]
	v_mfma_f32_16x16x32_bf16 v[70:73], v[166:169], v[216:219], v[70:73]
	v_mfma_f32_16x16x32_bf16 v[66:69], v[174:177], v[216:219], v[66:69]
.Lhalf_m0:
	s_setprio 0
	s_barrier
	s_add_i32 s81, s81, s2
	v_lshl_add_u64 v[148:149], s[58:59], 0, v[0:1]
	s_mov_b32 m0, s81
	s_cmp_eq_u32 s98, 1
	s_cbranch_scc1 .Lhalf_r1
	ds_read_b128 v[178:181], v153 offset:16384
	ds_read_b128 v[182:185], v153 offset:17408
	ds_read_b128 v[186:189], v153 offset:18432
	ds_read_b128 v[190:193], v153 offset:19456
	ds_read_b128 v[204:207], v153 offset:20480
	ds_read_b128 v[208:211], v153 offset:21504
	ds_read_b128 v[212:215], v153 offset:22528
	ds_read_b128 v[216:219], v153 offset:23552
; #define PG8_STAGE(bufoff, gbase, voff) do { _Pragma("unroll") for (int _i = 0; _i < 2; ++_i) \
;         __builtin_amdgcn_global_load_lds((const unsigned*)((const char*)(gbase) + (voff)[_i]), (PG8_LAS unsigned*)(lds + (bufoff) + ldsw + _i * 8192), 16, 0, 0); } while (0)
; #define PG8_LDA(dst, b, h) do { _Pragma("unroll") for (int m = 0; m < 4; ++m) _Pragma("unroll") for (int k = 0; k < 2; ++k) dst[m][k] = *(const PG8_LAS bf16x8*)(lds + PG8_SA(b, h) + aoff + m * 2048 + k * 1024); } while (0)
; #define PG8_LDB(dst, b, h) do { _Pragma("unroll") for (int n = 0; n < 2; ++n) _Pragma("unroll") for (int k = 0; k < 2; ++k) dst[n][k] = *(const PG8_LAS bf16x8*)(lds + PG8_SB(b, h) + boff + n * 2048 + k * 1024); } while (0)
; #define PG8_MMA(ai, bj, At, Bt) do { __builtin_amdgcn_s_setprio(1); _Pragma("unroll") for (int m = 0; m < 4; ++m) _Pragma("unroll") for (int n = 0; n < 2; ++n) _Pragma("unroll") for (int k = 0; k < 2; ++k) \
;         acc[ai][bj][m][n] = __builtin_amdgcn_mfma_f32_16x16x32_bf16(Bt[n][k], At[m][k], acc[ai][bj][m][n], 0, 0, 0); __builtin_amdgcn_s_setprio(0); } while (0)
; #define PG8_WAIT_V(n) asm volatile("s_waitcnt vmcnt(" #n ")" ::: "memory")
; #define PG8_WAIT_L(n) asm volatile("s_waitcnt lgkmcnt(" #n ")" ::: "memory")
; #define PG8_BAR __builtin_amdgcn_s_barrier()
; #define PG8_SCHED __builtin_amdgcn_sched_barrier(0)
; template <class Epi, class Sched, bool ALIGN_EPI = false, bool SP2 = false>
; __device__ __forceinline__ void gemm_phase(PG8_LAS unsigned char* lds, const Gemm g, const Sched& S, const Epi& E, int tid_in) {
;     ...
;             PG8_WAIT_V(8); PG8_WAIT_L(0); PG8_BAR; PG8_MMA(1, 0, At, B0); PG8_MMA(1, 1, At, B1); PG8_BAR; PG8_SCHED;
;             PG8_LDB(B0, 1, 0); PG8_LDB(B1, 1, 1); PG8_SCHED; PG8_LDA(At, 1, 0); PG8_STAGE(PG8_SA(0, 1), a2 + hstepA, voffA);
;             PG8_WAIT_V(8); PG8_WAIT_L(0); PG8_BAR; PG8_MMA(0, 0, At, B0); PG8_MMA(0, 1, At, B1); PG8_BAR; PG8_SCHED;
;             PG8_LDA(At, 1, 1); PG8_STAGE(PG8_SB(1, 0), b3, voffB); PG8_STAGE(PG8_SB(1, 1), b3 + hstep, voffB); PG8_STAGE(PG8_SA(1, 0), a3, voffA);
.Lhalf_r1:
	global_load_lds_dwordx4 v[148:149], off
	s_add_i32 m0, s81, 0x2000
	v_lshl_add_u64 v[194:195], s[58:59], 0, v[134:135]
	s_add_u32 s58, s58, s22
	s_addc_u32 s59, s59, s23
	s_add_i32 s15, s15, s2
	global_load_lds_dwordx4 v[194:195], off
	v_lshl_add_u64 v[220:221], s[58:59], 0, v[0:1]
	s_mov_b32 m0, s15
	v_lshl_add_u64 v[222:223], s[58:59], 0, v[134:135]
	global_load_lds_dwordx4 v[220:221], off
	s_add_i32 m0, s15, 0x2000
	v_lshl_add_u64 v[224:225], s[54:55], 0, v[130:131]
	global_load_lds_dwordx4 v[222:223], off
	s_mov_b32 m0, s62
	v_lshl_add_u64 v[226:227], s[54:55], 0, v[132:133]
	global_load_lds_dwordx4 v[224:225], off
	s_mov_b32 m0, s63
	s_nop 0
	global_load_lds_dwordx4 v[226:227], off
	s_waitcnt vmcnt(8)
	s_waitcnt lgkmcnt(0)
	s_barrier
	s_setprio 1
	s_waitcnt lgkmcnt(0)
	s_cmp_eq_u32 s98, 1
	s_cbranch_scc1 .Lhalf_m1
	v_mfma_f32_16x16x32_bf16 v[62:65], v[140:143], v[178:181], v[62:65]
	v_mfma_f32_16x16x32_bf16 v[58:61], v[154:157], v[178:181], v[58:61]
	v_mfma_f32_16x16x32_bf16 v[46:49], v[140:143], v[186:189], v[46:49]
	v_mfma_f32_16x16x32_bf16 v[42:45], v[154:157], v[186:189], v[42:45]
	v_mfma_f32_16x16x32_bf16 v[30:33], v[140:143], v[204:207], v[30:33]
	v_mfma_f32_16x16x32_bf16 v[26:29], v[154:157], v[204:207], v[26:29]
	v_mfma_f32_16x16x32_bf16 v[14:17], v[140:143], v[212:215], v[14:17]
	v_mfma_f32_16x16x32_bf16 v[10:13], v[154:157], v[212:215], v[10:13]
	v_mfma_f32_16x16x32_bf16 v[62:65], v[144:147], v[182:185], v[62:65]
	v_mfma_f32_16x16x32_bf16 v[58:61], v[158:161], v[182:185], v[58:61]
	v_mfma_f32_16x16x32_bf16 v[46:49], v[144:147], v[190:193], v[46:49]
	v_mfma_f32_16x16x32_bf16 v[42:45], v[158:161], v[190:193], v[42:45]
	v_mfma_f32_16x16x32_bf16 v[30:33], v[144:147], v[208:211], v[30:33]
	v_mfma_f32_16x16x32_bf16 v[26:29], v[158:161], v[208:211], v[26:29]
	v_mfma_f32_16x16x32_bf16 v[14:17], v[144:147], v[216:219], v[14:17]
	v_mfma_f32_16x16x32_bf16 v[10:13], v[158:161], v[216:219], v[10:13]
	s_setprio 0
	s_setprio 1
	v_mfma_f32_16x16x32_bf16 v[54:57], v[162:165], v[178:181], v[54:57]
	v_mfma_f32_16x16x32_bf16 v[50:53], v[170:173], v[178:181], v[50:53]
	v_mfma_f32_16x16x32_bf16 v[38:41], v[162:165], v[186:189], v[38:41]
	v_mfma_f32_16x16x32_bf16 v[34:37], v[170:173], v[186:189], v[34:37]
	v_mfma_f32_16x16x32_bf16 v[22:25], v[162:165], v[204:207], v[22:25]
	v_mfma_f32_16x16x32_bf16 v[18:21], v[170:173], v[204:207], v[18:21]
	v_mfma_f32_16x16x32_bf16 v[6:9], v[162:165], v[212:215], v[6:9]
	v_mfma_f32_16x16x32_bf16 v[2:5], v[170:173], v[212:215], v[2:5]
	v_mfma_f32_16x16x32_bf16 v[54:57], v[166:169], v[182:185], v[54:57]
	v_mfma_f32_16x16x32_bf16 v[50:53], v[174:177], v[182:185], v[50:53]
	v_mfma_f32_16x16x32_bf16 v[38:41], v[166:169], v[190:193], v[38:41]
	v_mfma_f32_16x16x32_bf16 v[34:37], v[174:177], v[190:193], v[34:37]
	v_mfma_f32_16x16x32_bf16 v[22:25], v[166:169], v[208:211], v[22:25]
	v_mfma_f32_16x16x32_bf16 v[18:21], v[174:177], v[208:211], v[18:21]
	v_mfma_f32_16x16x32_bf16 v[6:9], v[166:169], v[216:219], v[6:9]
	v_mfma_f32_16x16x32_bf16 v[2:5], v[174:177], v[216:219], v[2:5]
.Lhalf_m1:
	s_setprio 0
	s_barrier
	s_add_i32 s15, 0, 0x18000
	s_add_i32 s58, 0, 0x1c000
	v_add_u32_e32 v158, s15, v151
	v_add_u32_e32 v174, s58, v151
	ds_read_b128 v[140:143], v158
	ds_read_b128 v[144:147], v158 offset:1024
	ds_read_b128 v[154:157], v158 offset:2048
	ds_read_b128 v[158:161], v158 offset:3072
	ds_read_b128 v[162:165], v174
	ds_read_b128 v[166:169], v174 offset:1024
	ds_read_b128 v[170:173], v174 offset:2048
	ds_read_b128 v[174:177], v174 offset:3072
	s_add_u32 s54, s54, s22
	s_addc_u32 s55, s55, s23
	s_mov_b32 m0, s64
	v_lshl_add_u64 v[228:229], s[54:55], 0, v[130:131]
	s_cmp_eq_u32 s98, 2
	s_cbranch_scc1 .Lhalf_r2
	ds_read_b128 v[178:181], v153 offset:32768
	ds_read_b128 v[182:185], v153 offset:33792
	ds_read_b128 v[186:189], v153 offset:34816
	ds_read_b128 v[190:193], v153 offset:35840
	ds_read_b128 v[204:207], v153 offset:36864
	ds_read_b128 v[208:211], v153 offset:37888
	ds_read_b128 v[212:215], v153 offset:38912
	ds_read_b128 v[216:219], v153 offset:39936
; #define PG8_STAGE(bufoff, gbase, voff) do { _Pragma("unroll") for (int _i = 0; _i < 2; ++_i) \
;         __builtin_amdgcn_global_load_lds((const unsigned*)((const char*)(gbase) + (voff)[_i]), (PG8_LAS unsigned*)(lds + (bufoff) + ldsw + _i * 8192), 16, 0, 0); } while (0)
; #define PG8_LDA(dst, b, h) do { _Pragma("unroll") for (int m = 0; m < 4; ++m) _Pragma("unroll") for (int k = 0; k < 2; ++k) dst[m][k] = *(const PG8_LAS bf16x8*)(lds + PG8_SA(b, h) + aoff + m * 2048 + k * 1024); } while (0)
; #define PG8_LDB(dst, b, h) do { _Pragma("unroll") for (int n = 0; n < 2; ++n) _Pragma("unroll") for (int k = 0; k < 2; ++k) dst[n][k] = *(const PG8_LAS bf16x8*)(lds + PG8_SB(b, h) + boff + n * 2048 + k * 1024); } while (0)
; #define PG8_MMA(ai, bj, At, Bt) do { __builtin_amdgcn_s_setprio(1); _Pragma("unroll") for (int m = 0; m < 4; ++m) _Pragma("unroll") for (int n = 0; n < 2; ++n) _Pragma("unroll") for (int k = 0; k < 2; ++k) \
;         acc[ai][bj][m][n] = __builtin_amdgcn_mfma_f32_16x16x32_bf16(Bt[n][k], At[m][k], acc[ai][bj][m][n], 0, 0, 0); __builtin_amdgcn_s_setprio(0); } while (0)
; #define PG8_WAIT_V(n) asm volatile("s_waitcnt vmcnt(" #n ")" ::: "memory")
; #define PG8_WAIT_L(n) asm volatile("s_waitcnt lgkmcnt(" #n ")" ::: "memory")
; #define PG8_BAR __builtin_amdgcn_s_barrier()
; #define PG8_SCHED __builtin_amdgcn_sched_barrier(0)
; template <class Epi, class Sched, bool ALIGN_EPI = false, bool SP2 = false>
; __device__ __forceinline__ void gemm_phase(PG8_LAS unsigned char* lds, const Gemm g, const Sched& S, const Epi& E, int tid_in) {
;     ...
;             PG8_LDB(B0, 1, 0); PG8_LDB(B1, 1, 1); PG8_SCHED; PG8_LDA(At, 1, 0); PG8_STAGE(PG8_SA(0, 1), a2 + hstepA, voffA);
;             PG8_WAIT_V(8); PG8_WAIT_L(0); PG8_BAR; PG8_MMA(0, 0, At, B0); PG8_MMA(0, 1, At, B1); PG8_BAR; PG8_SCHED;
;             PG8_LDA(At, 1, 1); PG8_STAGE(PG8_SB(1, 0), b3, voffB); PG8_STAGE(PG8_SB(1, 1), b3 + hstep, voffB); PG8_STAGE(PG8_SA(1, 0), a3, voffA);
;             PG8_WAIT_V(8); PG8_WAIT_L(0); PG8_BAR; PG8_MMA(1, 0, At, B0); PG8_MMA(1, 1, At, B1); PG8_BAR; PG8_SCHED;
.Lhalf_r2:
	global_load_lds_dwordx4 v[228:229], off
	v_lshl_add_u64 v[228:229], s[54:55], 0, v[132:133]
	s_mov_b32 m0, s65
	s_nop 0
	global_load_lds_dwordx4 v[228:229], off
	s_waitcnt vmcnt(8)
	s_waitcnt lgkmcnt(0)
	s_barrier
	s_setprio 1
	s_waitcnt lgkmcnt(0)
	s_cmp_eq_u32 s98, 2
	s_cbranch_scc1 .Lhalf_m2
	v_mfma_f32_16x16x32_bf16 v[126:129], v[140:143], v[178:181], v[126:129]
	v_mfma_f32_16x16x32_bf16 v[122:125], v[154:157], v[178:181], v[122:125]
	v_mfma_f32_16x16x32_bf16 v[110:113], v[140:143], v[186:189], v[110:113]
	v_mfma_f32_16x16x32_bf16 v[106:109], v[154:157], v[186:189], v[106:109]
	v_mfma_f32_16x16x32_bf16 v[94:97], v[140:143], v[204:207], v[94:97]
	v_mfma_f32_16x16x32_bf16 v[90:93], v[154:157], v[204:207], v[90:93]
	v_mfma_f32_16x16x32_bf16 v[78:81], v[140:143], v[212:215], v[78:81]
	v_mfma_f32_16x16x32_bf16 v[74:77], v[154:157], v[212:215], v[74:77]
	v_mfma_f32_16x16x32_bf16 v[126:129], v[144:147], v[182:185], v[126:129]
	v_mfma_f32_16x16x32_bf16 v[122:125], v[158:161], v[182:185], v[122:125]
	v_mfma_f32_16x16x32_bf16 v[110:113], v[144:147], v[190:193], v[110:113]
	v_mfma_f32_16x16x32_bf16 v[106:109], v[158:161], v[190:193], v[106:109]
	v_mfma_f32_16x16x32_bf16 v[94:97], v[144:147], v[208:211], v[94:97]
	v_mfma_f32_16x16x32_bf16 v[90:93], v[158:161], v[208:211], v[90:93]
	v_mfma_f32_16x16x32_bf16 v[78:81], v[144:147], v[216:219], v[78:81]
	v_mfma_f32_16x16x32_bf16 v[74:77], v[158:161], v[216:219], v[74:77]
	s_setprio 0
	s_setprio 1
	v_mfma_f32_16x16x32_bf16 v[118:121], v[162:165], v[178:181], v[118:121]
	v_mfma_f32_16x16x32_bf16 v[114:117], v[170:173], v[178:181], v[114:117]
	v_mfma_f32_16x16x32_bf16 v[102:105], v[162:165], v[186:189], v[102:105]
	v_mfma_f32_16x16x32_bf16 v[98:101], v[170:173], v[186:189], v[98:101]
	v_mfma_f32_16x16x32_bf16 v[86:89], v[162:165], v[204:207], v[86:89]
	v_mfma_f32_16x16x32_bf16 v[82:85], v[170:173], v[204:207], v[82:85]
	v_mfma_f32_16x16x32_bf16 v[70:73], v[162:165], v[212:215], v[70:73]
	v_mfma_f32_16x16x32_bf16 v[66:69], v[170:173], v[212:215], v[66:69]
	v_mfma_f32_16x16x32_bf16 v[118:121], v[166:169], v[182:185], v[118:121]
	v_mfma_f32_16x16x32_bf16 v[114:117], v[174:177], v[182:185], v[114:117]
	v_mfma_f32_16x16x32_bf16 v[102:105], v[166:169], v[190:193], v[102:105]
	v_mfma_f32_16x16x32_bf16 v[98:101], v[174:177], v[190:193], v[98:101]
	v_mfma_f32_16x16x32_bf16 v[86:89], v[166:169], v[208:211], v[86:89]
	v_mfma_f32_16x16x32_bf16 v[82:85], v[174:177], v[208:211], v[82:85]
	v_mfma_f32_16x16x32_bf16 v[70:73], v[166:169], v[216:219], v[70:73]
	v_mfma_f32_16x16x32_bf16 v[66:69], v[174:177], v[216:219], v[66:69]
.Lhalf_m2:
	s_setprio 0
	s_barrier
	s_add_i32 s15, s15, s2
	v_lshl_add_u64 v[148:149], v[148:149], 0, s[28:29]
	s_mov_b32 m0, s15
	s_cmp_eq_u32 s98, 1
	s_cbranch_scc1 .Lhalf_r3
	ds_read_b128 v[178:181], v153 offset:49152
	ds_read_b128 v[182:185], v153 offset:50176
	ds_read_b128 v[186:189], v153 offset:51200
	ds_read_b128 v[190:193], v153 offset:52224
	ds_read_b128 v[204:207], v153 offset:53248
	ds_read_b128 v[208:211], v153 offset:54272
	ds_read_b128 v[212:215], v153 offset:55296
	ds_read_b128 v[216:219], v153 offset:56320
.Lhalf_r3:
	global_load_lds_dwordx4 v[148:149], off
	v_lshl_add_u64 v[148:149], v[194:195], 0, s[28:29]
	s_add_i32 m0, s15, 0x2000
	s_add_i32 s15, s58, s2
	global_load_lds_dwordx4 v[148:149], off
	v_lshl_add_u64 v[148:149], v[220:221], 0, s[28:29]
	s_mov_b32 m0, s15
	s_nop 0
	global_load_lds_dwordx4 v[148:149], off
	v_lshl_add_u64 v[148:149], v[222:223], 0, s[28:29]
	s_add_i32 m0, s15, 0x2000
	s_nop 0
	global_load_lds_dwordx4 v[148:149], off
	v_lshl_add_u64 v[148:149], v[224:225], 0, s[28:29]
	s_mov_b32 m0, s66
	s_nop 0
	global_load_lds_dwordx4 v[148:149], off
	v_lshl_add_u64 v[148:149], v[226:227], 0, s[28:29]
	s_mov_b32 m0, s67
	s_nop 0
	global_load_lds_dwordx4 v[148:149], off
	s_waitcnt vmcnt(8)
	s_waitcnt lgkmcnt(0)
	s_barrier
	s_setprio 1
	s_waitcnt lgkmcnt(0)
	s_cmp_eq_u32 s98, 1
	s_cbranch_scc1 .Lhalf_m3
	v_mfma_f32_16x16x32_bf16 v[62:65], v[140:143], v[178:181], v[62:65]
	v_mfma_f32_16x16x32_bf16 v[58:61], v[154:157], v[178:181], v[58:61]
	v_mfma_f32_16x16x32_bf16 v[46:49], v[140:143], v[186:189], v[46:49]
	v_mfma_f32_16x16x32_bf16 v[42:45], v[154:157], v[186:189], v[42:45]
	v_mfma_f32_16x16x32_bf16 v[30:33], v[140:143], v[204:207], v[30:33]
	v_mfma_f32_16x16x32_bf16 v[26:29], v[154:157], v[204:207], v[26:29]
	v_mfma_f32_16x16x32_bf16 v[14:17], v[140:143], v[212:215], v[14:17]
	v_mfma_f32_16x16x32_bf16 v[10:13], v[154:157], v[212:215], v[10:13]
	v_mfma_f32_16x16x32_bf16 v[62:65], v[144:147], v[182:185], v[62:65]
	v_mfma_f32_16x16x32_bf16 v[58:61], v[158:161], v[182:185], v[58:61]
	v_mfma_f32_16x16x32_bf16 v[46:49], v[144:147], v[190:193], v[46:49]
	v_mfma_f32_16x16x32_bf16 v[42:45], v[158:161], v[190:193], v[42:45]
	v_mfma_f32_16x16x32_bf16 v[30:33], v[144:147], v[208:211], v[30:33]
	v_mfma_f32_16x16x32_bf16 v[26:29], v[158:161], v[208:211], v[26:29]
	v_mfma_f32_16x16x32_bf16 v[14:17], v[144:147], v[216:219], v[14:17]
	v_mfma_f32_16x16x32_bf16 v[10:13], v[158:161], v[216:219], v[10:13]
	s_setprio 0
	s_setprio 1
	v_mfma_f32_16x16x32_bf16 v[54:57], v[162:165], v[178:181], v[54:57]
	v_mfma_f32_16x16x32_bf16 v[50:53], v[170:173], v[178:181], v[50:53]
	v_mfma_f32_16x16x32_bf16 v[38:41], v[162:165], v[186:189], v[38:41]
	v_mfma_f32_16x16x32_bf16 v[34:37], v[170:173], v[186:189], v[34:37]
	v_mfma_f32_16x16x32_bf16 v[22:25], v[162:165], v[204:207], v[22:25]
	v_mfma_f32_16x16x32_bf16 v[18:21], v[170:173], v[204:207], v[18:21]
	v_mfma_f32_16x16x32_bf16 v[6:9], v[162:165], v[212:215], v[6:9]
	v_mfma_f32_16x16x32_bf16 v[2:5], v[170:173], v[212:215], v[2:5]
	v_mfma_f32_16x16x32_bf16 v[54:57], v[166:169], v[182:185], v[54:57]
	v_mfma_f32_16x16x32_bf16 v[50:53], v[174:177], v[182:185], v[50:53]
	v_mfma_f32_16x16x32_bf16 v[38:41], v[166:169], v[190:193], v[38:41]
	v_mfma_f32_16x16x32_bf16 v[34:37], v[174:177], v[190:193], v[34:37]
	v_mfma_f32_16x16x32_bf16 v[22:25], v[166:169], v[208:211], v[22:25]
	v_mfma_f32_16x16x32_bf16 v[18:21], v[174:177], v[208:211], v[18:21]
	v_mfma_f32_16x16x32_bf16 v[6:9], v[166:169], v[216:219], v[6:9]
	v_mfma_f32_16x16x32_bf16 v[2:5], v[174:177], v[216:219], v[2:5]
.Lhalf_m3:
	s_setprio 0
	s_barrier
	s_add_u32 s52, s52, 0x100
	s_addc_u32 s53, s53, 0
	s_add_u32 s12, s12, 0x100
	s_addc_u32 s13, s13, 0
	s_cmp_ge_i32 s57, s69
	s_mov_b32 s15, s57
	s_cbranch_scc0 .LBB0_542
	s_movk_i32 s81, 0x4040

; __device__ __forceinline__ u32x4 pack8(const f32x4 a, const f32x4 b) { u32x4 w; w.x = cvt_pk_bf16(a[0], a[1]); w.y = cvt_pk_bf16(a[2], a[3]); w.z = cvt_pk_bf16(b[0], b[1]); w.w = cvt_pk_bf16(b[2], b[3]); return w; }
;     __device__ __forceinline__ void operator()(const f32x4 (&acc)[2][2][4][2], const Unit& u, int wr, int wc, int fr, int fq) const {
;     ...
;             for (int m = 0; m < 4; ++m) { const int row = row0 + u.pm * 256 + ai * 128 + wr * 64 + m * 16 + fr; const bool pad = row_is_pad(row); float s = 0.f;
; #pragma unroll
;                 for (int bj = 0; bj < 2; ++bj) { const size_t off = (size_t)row * 1024 + col0 + bj * 128; const u32x4 hv = __builtin_nontemporal_load((const u32x4*)(hin + off));
;                     f32x4 v0 = acc[ai][bj][m][0], v1 = acc[ai][bj][m][1];
;                     v0[0] += __uint_as_float(hv.x << 16); v0[1] += __uint_as_float(hv.x & 0xffff0000u); v0[2] += __uint_as_float(hv.y << 16); v0[3] += __uint_as_float(hv.y & 0xffff0000u);
;                     v1[0] += __uint_as_float(hv.z << 16); v1[1] += __uint_as_float(hv.z & 0xffff0000u); v1[2] += __uint_as_float(hv.w << 16); v1[3] += __uint_as_float(hv.w & 0xffff0000u);
; #pragma unroll
;                     for (int e = 0; e < 4; ++e) s += v0[e] * v0[e] + v1[e] * v1[e];
;                     if (!pad) *(u32x4*)(hout + off) = pack8(v0, v1); }
;                 s += __shfl_xor(s, 16); s += __shfl_xor(s, 32);
;                 if (fq == 0) ssq[(size_t)row * 16 + u.pn * 4 + wc] = pad ? 0.f : s;
.LBB0_552:
	s_or_b64 exec, exec, s[12:13]
	s_and_saveexec_b64 s[12:13], s[52:53]
	v_cmp_gt_i32_e32 vcc, 48, v140
	s_orn2_b64 s[54:55], vcc, exec
	s_or_b64 exec, exec, s[12:13]
	v_lshl_or_b32 v140, s24, 8, v152
	v_ashrrev_i32_e32 v143, 31, v142
	v_ashrrev_i32_e32 v141, 31, v140
	v_lshlrev_b64 v[144:145], 10, v[142:143]
	v_lshl_add_u64 v[156:157], v[144:145], 0, v[140:141]
	v_lshl_add_u64 v[148:149], v[156:157], 1, s[4:5]
	s_nop 1
	s_xor_b64 s[12:13], s[54:55], -1
	v_lshl_add_u64 v[144:145], v[156:157], 1, s[0:1]
	s_and_saveexec_b64 s[52:53], s[12:13]
	s_cbranch_execz .LBB0_556
	v_cvt_pk_bf16_f32 v156, v126, v127
	v_cvt_pk_bf16_f32 v157, v128, v129
	v_cvt_pk_bf16_f32 v158, v122, v123
	v_cvt_pk_bf16_f32 v159, v124, v125
	s_cmp_eq_u32 s98, 2
	s_cselect_b64 exec, 0, exec
	global_store_dwordx4 v[144:145], v[156:159], off
.LBB0_556:
	s_or_b64 exec, exec, s[52:53]
	s_nop 1
	s_and_saveexec_b64 s[52:53], s[12:13]
	s_cbranch_execz .LBB0_558
	v_cvt_pk_bf16_f32 v146, v118, v119
	v_cvt_pk_bf16_f32 v147, v120, v121
	v_cvt_pk_bf16_f32 v148, v114, v115
	v_cvt_pk_bf16_f32 v149, v116, v117
	s_cmp_eq_u32 s98, 2
	s_cselect_b64 exec, 0, exec
	global_store_dwordx4 v[144:145], v[146:149], off offset:256
.LBB0_558:
	s_or_b64 exec, exec, s[52:53]
	v_pk_mul_f32 v[122:123], v[122:123], v[122:123]
	v_pk_mul_f32 v[124:125], v[124:125], v[124:125]
	v_pk_fma_f32 v[122:123], v[126:127], v[126:127], v[122:123]
	v_pk_mul_f32 v[114:115], v[114:115], v[114:115]
	v_pk_fma_f32 v[124:125], v[128:129], v[128:129], v[124:125]
	v_pk_fma_f32 v[114:115], v[118:119], v[118:119], v[114:115]
	v_add_f32_e32 v118, v122, v123
	v_add_f32_e32 v118, v124, v118
	v_add_f32_e32 v118, v125, v118
	v_pk_mul_f32 v[116:117], v[116:117], v[116:117]
	v_add_f32_e32 v114, v118, v114
	v_pk_fma_f32 v[116:117], v[120:121], v[120:121], v[116:117]
	v_add_f32_e32 v114, v115, v114
	v_add_f32_e32 v114, v116, v114
	v_and_b32_e32 v116, 64, v198
	v_xor_b32_e32 v115, 16, v198
	v_add_u32_e32 v116, 64, v116
	v_cmp_lt_i32_e32 vcc, v115, v116
	v_add_f32_e32 v114, v117, v114
	v_xor_b32_e32 v117, 32, v198
	v_cndmask_b32_e32 v115, v198, v115, vcc
	v_lshlrev_b32_e32 v120, 2, v115
	ds_bpermute_b32 v115, v120, v114
	v_cmp_lt_i32_e32 vcc, v117, v116
	s_lshl_b32 s52, s24, 2
	s_ashr_i32 s53, s52, 31
	v_cndmask_b32_e32 v116, v198, v117, vcc
	v_lshlrev_b32_e32 v121, 2, v116
	s_waitcnt lgkmcnt(0)
	v_add_f32_e32 v114, v114, v115
	ds_bpermute_b32 v115, v121, v114
	s_and_saveexec_b64 s[12:13], s[36:37]
	s_cbranch_execz .LBB0_560
	v_lshlrev_b64 v[116:117], 6, v[142:143]
	v_lshl_add_u64 v[116:117], s[10:11], 0, v[116:117]
	v_lshl_add_u64 v[116:117], s[52:53], 2, v[116:117]
	s_lshl_b32 s24, s68, 2
	s_waitcnt lgkmcnt(0)
	v_add_f32_e32 v114, v114, v115
	v_lshl_add_u64 v[116:117], v[116:117], 0, s[24:25]
	v_cndmask_b32_e64 v114, v114, 0, s[54:55]
	s_cmp_eq_u32 s98, 2
	s_cselect_b64 exec, 0, exec
	global_store_dword v[116:117], v114, off

; __device__ __forceinline__ u32x4 pack8(const f32x4 a, const f32x4 b) { u32x4 w; w.x = cvt_pk_bf16(a[0], a[1]); w.y = cvt_pk_bf16(a[2], a[3]); w.z = cvt_pk_bf16(b[0], b[1]); w.w = cvt_pk_bf16(b[2], b[3]); return w; }
;     __device__ __forceinline__ void operator()(const f32x4 (&acc)[2][2][4][2], const Unit& u, int wr, int wc, int fr, int fq) const {
;     ...
;             for (int m = 0; m < 4; ++m) { const int row = row0 + u.pm * 256 + ai * 128 + wr * 64 + m * 16 + fr; const bool pad = row_is_pad(row); float s = 0.f;
; #pragma unroll
;                 for (int bj = 0; bj < 2; ++bj) { const size_t off = (size_t)row * 1024 + col0 + bj * 128; const u32x4 hv = __builtin_nontemporal_load((const u32x4*)(hin + off));
;                     f32x4 v0 = acc[ai][bj][m][0], v1 = acc[ai][bj][m][1];
;                     v0[0] += __uint_as_float(hv.x << 16); v0[1] += __uint_as_float(hv.x & 0xffff0000u); v0[2] += __uint_as_float(hv.y << 16); v0[3] += __uint_as_float(hv.y & 0xffff0000u);
;                     v1[0] += __uint_as_float(hv.z << 16); v1[1] += __uint_as_float(hv.z & 0xffff0000u); v1[2] += __uint_as_float(hv.w << 16); v1[3] += __uint_as_float(hv.w & 0xffff0000u);
; #pragma unroll
;                     for (int e = 0; e < 4; ++e) s += v0[e] * v0[e] + v1[e] * v1[e];
;                     if (!pad) *(u32x4*)(hout + off) = pack8(v0, v1); }
;                 s += __shfl_xor(s, 16); s += __shfl_xor(s, 32);
;                 if (fq == 0) ssq[(size_t)row * 16 + u.pn * 4 + wc] = pad ? 0.f : s;
.LBB0_566:
	s_or_b64 exec, exec, s[12:13]
	s_and_saveexec_b64 s[12:13], s[56:57]
	v_cmp_gt_i32_e32 vcc, 48, v115
	s_orn2_b64 s[54:55], vcc, exec
	s_or_b64 exec, exec, s[12:13]
	v_ashrrev_i32_e32 v115, 31, v114
	v_lshlrev_b64 v[116:117], 10, v[114:115]
	v_lshl_add_u64 v[116:117], v[116:117], 0, v[140:141]
	v_lshl_add_u64 v[118:119], v[116:117], 1, s[4:5]
	s_nop 1
	s_xor_b64 s[12:13], s[54:55], -1
	v_lshl_add_u64 v[116:117], v[116:117], 1, s[0:1]
	s_and_saveexec_b64 s[56:57], s[12:13]
	s_cbranch_execz .LBB0_570
	v_cvt_pk_bf16_f32 v122, v110, v111
	v_cvt_pk_bf16_f32 v123, v112, v113
	v_cvt_pk_bf16_f32 v124, v106, v107
	v_cvt_pk_bf16_f32 v125, v108, v109
	s_cmp_eq_u32 s98, 2
	s_cselect_b64 exec, 0, exec
	global_store_dwordx4 v[116:117], v[122:125], off
.LBB0_570:
	s_or_b64 exec, exec, s[56:57]
	s_nop 1
	s_and_saveexec_b64 s[56:57], s[12:13]
	s_cbranch_execz .LBB0_572
	v_cvt_pk_bf16_f32 v122, v102, v103
	v_cvt_pk_bf16_f32 v123, v104, v105
	v_cvt_pk_bf16_f32 v124, v98, v99
	v_cvt_pk_bf16_f32 v125, v100, v101
	s_cmp_eq_u32 s98, 2
	s_cselect_b64 exec, 0, exec
	global_store_dwordx4 v[116:117], v[122:125], off offset:256
.LBB0_572:
	s_or_b64 exec, exec, s[56:57]
	v_pk_mul_f32 v[106:107], v[106:107], v[106:107]
	v_pk_mul_f32 v[108:109], v[108:109], v[108:109]
	v_pk_fma_f32 v[106:107], v[110:111], v[110:111], v[106:107]
	v_pk_mul_f32 v[98:99], v[98:99], v[98:99]
	v_pk_fma_f32 v[108:109], v[112:113], v[112:113], v[108:109]
	v_pk_fma_f32 v[98:99], v[102:103], v[102:103], v[98:99]
	v_add_f32_e32 v102, v106, v107
	v_add_f32_e32 v102, v108, v102
	v_add_f32_e32 v102, v109, v102
	v_pk_mul_f32 v[100:101], v[100:101], v[100:101]
	v_add_f32_e32 v98, v102, v98
	v_pk_fma_f32 v[100:101], v[104:105], v[104:105], v[100:101]
	v_add_f32_e32 v98, v99, v98
	v_add_f32_e32 v98, v100, v98
	v_add_f32_e32 v98, v101, v98
	ds_bpermute_b32 v99, v120, v98
	s_waitcnt lgkmcnt(0)
	v_add_f32_e32 v98, v98, v99
	ds_bpermute_b32 v99, v121, v98
	s_and_saveexec_b64 s[12:13], s[36:37]
	s_cbranch_execz .LBB0_574
	v_lshlrev_b64 v[100:101], 6, v[114:115]
	v_lshl_add_u64 v[100:101], s[10:11], 0, v[100:101]
	v_lshl_add_u64 v[100:101], s[52:53], 2, v[100:101]
	s_lshl_b32 s24, s68, 2
	s_waitcnt lgkmcnt(0)
	v_add_f32_e32 v98, v98, v99
	v_lshl_add_u64 v[100:101], v[100:101], 0, s[24:25]
	v_cndmask_b32_e64 v98, v98, 0, s[54:55]
	s_cmp_eq_u32 s98, 2
	s_cselect_b64 exec, 0, exec
	global_store_dword v[100:101], v98, off

; __device__ __forceinline__ u32x4 pack8(const f32x4 a, const f32x4 b) { u32x4 w; w.x = cvt_pk_bf16(a[0], a[1]); w.y = cvt_pk_bf16(a[2], a[3]); w.z = cvt_pk_bf16(b[0], b[1]); w.w = cvt_pk_bf16(b[2], b[3]); return w; }
;     __device__ __forceinline__ void operator()(const f32x4 (&acc)[2][2][4][2], const Unit& u, int wr, int wc, int fr, int fq) const {
;     ...
;             for (int m = 0; m < 4; ++m) { const int row = row0 + u.pm * 256 + ai * 128 + wr * 64 + m * 16 + fr; const bool pad = row_is_pad(row); float s = 0.f;
; #pragma unroll
;                 for (int bj = 0; bj < 2; ++bj) { const size_t off = (size_t)row * 1024 + col0 + bj * 128; const u32x4 hv = __builtin_nontemporal_load((const u32x4*)(hin + off));
;                     f32x4 v0 = acc[ai][bj][m][0], v1 = acc[ai][bj][m][1];
;                     v0[0] += __uint_as_float(hv.x << 16); v0[1] += __uint_as_float(hv.x & 0xffff0000u); v0[2] += __uint_as_float(hv.y << 16); v0[3] += __uint_as_float(hv.y & 0xffff0000u);
;                     v1[0] += __uint_as_float(hv.z << 16); v1[1] += __uint_as_float(hv.z & 0xffff0000u); v1[2] += __uint_as_float(hv.w << 16); v1[3] += __uint_as_float(hv.w & 0xffff0000u);
; #pragma unroll
;                     for (int e = 0; e < 4; ++e) s += v0[e] * v0[e] + v1[e] * v1[e];
;                     if (!pad) *(u32x4*)(hout + off) = pack8(v0, v1); }
;                 s += __shfl_xor(s, 16); s += __shfl_xor(s, 32);
;                 if (fq == 0) ssq[(size_t)row * 16 + u.pn * 4 + wc] = pad ? 0.f : s;
.LBB0_580:
	s_or_b64 exec, exec, s[12:13]
	s_and_saveexec_b64 s[12:13], s[56:57]
	v_cmp_gt_i32_e32 vcc, 48, v99
	s_orn2_b64 s[54:55], vcc, exec
	s_or_b64 exec, exec, s[12:13]
	v_ashrrev_i32_e32 v99, 31, v98
	v_lshlrev_b64 v[100:101], 10, v[98:99]
	v_lshl_add_u64 v[100:101], v[100:101], 0, v[140:141]
	v_lshl_add_u64 v[102:103], v[100:101], 1, s[4:5]
	s_nop 1
	s_xor_b64 s[12:13], s[54:55], -1
	v_lshl_add_u64 v[100:101], v[100:101], 1, s[0:1]
	s_and_saveexec_b64 s[56:57], s[12:13]
	s_cbranch_execz .LBB0_584
	v_cvt_pk_bf16_f32 v104, v94, v95
	v_cvt_pk_bf16_f32 v105, v96, v97
	v_cvt_pk_bf16_f32 v106, v90, v91
	v_cvt_pk_bf16_f32 v107, v92, v93
	s_cmp_eq_u32 s98, 2
	s_cselect_b64 exec, 0, exec
	global_store_dwordx4 v[100:101], v[104:107], off
.LBB0_584:
	s_or_b64 exec, exec, s[56:57]
	s_nop 1
	s_and_saveexec_b64 s[56:57], s[12:13]
	s_cbranch_execz .LBB0_586
	v_cvt_pk_bf16_f32 v102, v86, v87
	v_cvt_pk_bf16_f32 v103, v88, v89
	v_cvt_pk_bf16_f32 v104, v82, v83
	v_cvt_pk_bf16_f32 v105, v84, v85
	s_cmp_eq_u32 s98, 2
	s_cselect_b64 exec, 0, exec
	global_store_dwordx4 v[100:101], v[102:105], off offset:256
.LBB0_586:
	s_or_b64 exec, exec, s[56:57]
	v_pk_mul_f32 v[90:91], v[90:91], v[90:91]
	v_pk_mul_f32 v[92:93], v[92:93], v[92:93]
	v_pk_fma_f32 v[90:91], v[94:95], v[94:95], v[90:91]
	v_pk_mul_f32 v[82:83], v[82:83], v[82:83]
	v_pk_fma_f32 v[92:93], v[96:97], v[96:97], v[92:93]
	v_pk_fma_f32 v[82:83], v[86:87], v[86:87], v[82:83]
	v_add_f32_e32 v86, v90, v91
	v_add_f32_e32 v86, v92, v86
	v_add_f32_e32 v86, v93, v86
	v_pk_mul_f32 v[84:85], v[84:85], v[84:85]
	v_add_f32_e32 v82, v86, v82
	v_pk_fma_f32 v[84:85], v[88:89], v[88:89], v[84:85]
	v_add_f32_e32 v82, v83, v82
	v_add_f32_e32 v82, v84, v82
	v_add_f32_e32 v82, v85, v82
	ds_bpermute_b32 v83, v120, v82
	s_waitcnt lgkmcnt(0)
	v_add_f32_e32 v82, v82, v83
	ds_bpermute_b32 v83, v121, v82
	s_and_saveexec_b64 s[12:13], s[36:37]
	s_cbranch_execz .LBB0_588
	v_lshlrev_b64 v[84:85], 6, v[98:99]
	v_lshl_add_u64 v[84:85], s[10:11], 0, v[84:85]
	v_lshl_add_u64 v[84:85], s[52:53], 2, v[84:85]
	s_lshl_b32 s24, s68, 2
	s_waitcnt lgkmcnt(0)
	v_add_f32_e32 v82, v82, v83
	v_lshl_add_u64 v[84:85], v[84:85], 0, s[24:25]
	v_cndmask_b32_e64 v82, v82, 0, s[54:55]
	s_cmp_eq_u32 s98, 2
	s_cselect_b64 exec, 0, exec
	global_store_dword v[84:85], v82, off

; __device__ __forceinline__ u32x4 pack8(const f32x4 a, const f32x4 b) { u32x4 w; w.x = cvt_pk_bf16(a[0], a[1]); w.y = cvt_pk_bf16(a[2], a[3]); w.z = cvt_pk_bf16(b[0], b[1]); w.w = cvt_pk_bf16(b[2], b[3]); return w; }
;     __device__ __forceinline__ void operator()(const f32x4 (&acc)[2][2][4][2], const Unit& u, int wr, int wc, int fr, int fq) const {
;     ...
;             for (int m = 0; m < 4; ++m) { const int row = row0 + u.pm * 256 + ai * 128 + wr * 64 + m * 16 + fr; const bool pad = row_is_pad(row); float s = 0.f;
; #pragma unroll
;                 for (int bj = 0; bj < 2; ++bj) { const size_t off = (size_t)row * 1024 + col0 + bj * 128; const u32x4 hv = __builtin_nontemporal_load((const u32x4*)(hin + off));
;                     f32x4 v0 = acc[ai][bj][m][0], v1 = acc[ai][bj][m][1];
;                     v0[0] += __uint_as_float(hv.x << 16); v0[1] += __uint_as_float(hv.x & 0xffff0000u); v0[2] += __uint_as_float(hv.y << 16); v0[3] += __uint_as_float(hv.y & 0xffff0000u);
;                     v1[0] += __uint_as_float(hv.z << 16); v1[1] += __uint_as_float(hv.z & 0xffff0000u); v1[2] += __uint_as_float(hv.w << 16); v1[3] += __uint_as_float(hv.w & 0xffff0000u);
; #pragma unroll
;                     for (int e = 0; e < 4; ++e) s += v0[e] * v0[e] + v1[e] * v1[e];
;                     if (!pad) *(u32x4*)(hout + off) = pack8(v0, v1); }
;                 s += __shfl_xor(s, 16); s += __shfl_xor(s, 32);
;                 if (fq == 0) ssq[(size_t)row * 16 + u.pn * 4 + wc] = pad ? 0.f : s;
.LBB0_594:
	s_or_b64 exec, exec, s[12:13]
	s_and_saveexec_b64 s[12:13], s[56:57]
	v_cmp_gt_i32_e32 vcc, 48, v83
	s_orn2_b64 s[54:55], vcc, exec
	s_or_b64 exec, exec, s[12:13]
	v_ashrrev_i32_e32 v83, 31, v82
	v_lshlrev_b64 v[84:85], 10, v[82:83]
	v_lshl_add_u64 v[84:85], v[84:85], 0, v[140:141]
	v_lshl_add_u64 v[86:87], v[84:85], 1, s[4:5]
	s_nop 1
	s_xor_b64 s[12:13], s[54:55], -1
	v_lshl_add_u64 v[84:85], v[84:85], 1, s[0:1]
	s_and_saveexec_b64 s[56:57], s[12:13]
	s_cbranch_execz .LBB0_598
	v_cvt_pk_bf16_f32 v88, v78, v79
	v_cvt_pk_bf16_f32 v89, v80, v81
	v_cvt_pk_bf16_f32 v90, v74, v75
	v_cvt_pk_bf16_f32 v91, v76, v77
	s_cmp_eq_u32 s98, 2
	s_cselect_b64 exec, 0, exec
	global_store_dwordx4 v[84:85], v[88:91], off
.LBB0_598:
	s_or_b64 exec, exec, s[56:57]
	s_nop 1
	s_and_saveexec_b64 s[56:57], s[12:13]
	s_cbranch_execz .LBB0_600
	v_cvt_pk_bf16_f32 v86, v70, v71
	v_cvt_pk_bf16_f32 v87, v72, v73
	v_cvt_pk_bf16_f32 v88, v66, v67
	v_cvt_pk_bf16_f32 v89, v68, v69
	s_cmp_eq_u32 s98, 2
	s_cselect_b64 exec, 0, exec
	global_store_dwordx4 v[84:85], v[86:89], off offset:256
.LBB0_600:
	s_or_b64 exec, exec, s[56:57]
	v_pk_mul_f32 v[74:75], v[74:75], v[74:75]
	v_pk_mul_f32 v[76:77], v[76:77], v[76:77]
	v_pk_fma_f32 v[74:75], v[78:79], v[78:79], v[74:75]
	v_pk_mul_f32 v[66:67], v[66:67], v[66:67]
	v_pk_fma_f32 v[76:77], v[80:81], v[80:81], v[76:77]
	v_pk_fma_f32 v[66:67], v[70:71], v[70:71], v[66:67]
	v_add_f32_e32 v70, v74, v75
	v_add_f32_e32 v70, v76, v70
	v_add_f32_e32 v70, v77, v70
	v_pk_mul_f32 v[68:69], v[68:69], v[68:69]
	v_add_f32_e32 v66, v70, v66
	v_pk_fma_f32 v[68:69], v[72:73], v[72:73], v[68:69]
	v_add_f32_e32 v66, v67, v66
	v_add_f32_e32 v66, v68, v66
	v_add_f32_e32 v66, v69, v66
	ds_bpermute_b32 v67, v120, v66
	s_waitcnt lgkmcnt(0)
	v_add_f32_e32 v66, v66, v67
	ds_bpermute_b32 v67, v121, v66
	s_and_saveexec_b64 s[12:13], s[36:37]
	s_cbranch_execz .LBB0_602
	v_lshlrev_b64 v[68:69], 6, v[82:83]
	v_lshl_add_u64 v[68:69], s[10:11], 0, v[68:69]
	v_lshl_add_u64 v[68:69], s[52:53], 2, v[68:69]
	s_lshl_b32 s24, s68, 2
	s_waitcnt lgkmcnt(0)
	v_add_f32_e32 v66, v66, v67
	v_lshl_add_u64 v[68:69], v[68:69], 0, s[24:25]
	v_cndmask_b32_e64 v66, v66, 0, s[54:55]
	s_cmp_eq_u32 s98, 2
	s_cselect_b64 exec, 0, exec
	global_store_dword v[68:69], v66, off

; __device__ __forceinline__ u32x4 pack8(const f32x4 a, const f32x4 b) { u32x4 w; w.x = cvt_pk_bf16(a[0], a[1]); w.y = cvt_pk_bf16(a[2], a[3]); w.z = cvt_pk_bf16(b[0], b[1]); w.w = cvt_pk_bf16(b[2], b[3]); return w; }
;     __device__ __forceinline__ void operator()(const f32x4 (&acc)[2][2][4][2], const Unit& u, int wr, int wc, int fr, int fq) const {
;     ...
;             for (int m = 0; m < 4; ++m) { const int row = row0 + u.pm * 256 + ai * 128 + wr * 64 + m * 16 + fr; const bool pad = row_is_pad(row); float s = 0.f;
; #pragma unroll
;                 for (int bj = 0; bj < 2; ++bj) { const size_t off = (size_t)row * 1024 + col0 + bj * 128; const u32x4 hv = __builtin_nontemporal_load((const u32x4*)(hin + off));
;                     f32x4 v0 = acc[ai][bj][m][0], v1 = acc[ai][bj][m][1];
;                     v0[0] += __uint_as_float(hv.x << 16); v0[1] += __uint_as_float(hv.x & 0xffff0000u); v0[2] += __uint_as_float(hv.y << 16); v0[3] += __uint_as_float(hv.y & 0xffff0000u);
;                     v1[0] += __uint_as_float(hv.z << 16); v1[1] += __uint_as_float(hv.z & 0xffff0000u); v1[2] += __uint_as_float(hv.w << 16); v1[3] += __uint_as_float(hv.w & 0xffff0000u);
; #pragma unroll
;                     for (int e = 0; e < 4; ++e) s += v0[e] * v0[e] + v1[e] * v1[e];
;                     if (!pad) *(u32x4*)(hout + off) = pack8(v0, v1); }
;                 s += __shfl_xor(s, 16); s += __shfl_xor(s, 32);
;                 if (fq == 0) ssq[(size_t)row * 16 + u.pn * 4 + wc] = pad ? 0.f : s;
.LBB0_608:
	s_or_b64 exec, exec, s[12:13]
	s_and_saveexec_b64 s[12:13], s[56:57]
	v_cmp_gt_i32_e32 vcc, 48, v67
	s_orn2_b64 s[54:55], vcc, exec
	s_or_b64 exec, exec, s[12:13]
	v_ashrrev_i32_e32 v67, 31, v66
	v_lshlrev_b64 v[68:69], 10, v[66:67]
	v_lshl_add_u64 v[68:69], v[68:69], 0, v[140:141]
	v_lshl_add_u64 v[70:71], v[68:69], 1, s[4:5]
	s_nop 1
	s_xor_b64 s[12:13], s[54:55], -1
	v_lshl_add_u64 v[68:69], v[68:69], 1, s[0:1]
	s_and_saveexec_b64 s[56:57], s[12:13]
	s_cbranch_execz .LBB0_612
	v_cvt_pk_bf16_f32 v72, v62, v63
	v_cvt_pk_bf16_f32 v73, v64, v65
	v_cvt_pk_bf16_f32 v74, v58, v59
	v_cvt_pk_bf16_f32 v75, v60, v61
	s_cmp_eq_u32 s98, 1
	s_cselect_b64 exec, 0, exec
	global_store_dwordx4 v[68:69], v[72:75], off
.LBB0_612:
	s_or_b64 exec, exec, s[56:57]
	s_nop 1
	s_and_saveexec_b64 s[56:57], s[12:13]
	s_cbranch_execz .LBB0_614
	v_cvt_pk_bf16_f32 v70, v54, v55
	v_cvt_pk_bf16_f32 v71, v56, v57
	v_cvt_pk_bf16_f32 v72, v50, v51
	v_cvt_pk_bf16_f32 v73, v52, v53
	s_cmp_eq_u32 s98, 1
	s_cselect_b64 exec, 0, exec
	global_store_dwordx4 v[68:69], v[70:73], off offset:256
.LBB0_614:
	s_or_b64 exec, exec, s[56:57]
	v_pk_mul_f32 v[58:59], v[58:59], v[58:59]
	v_pk_mul_f32 v[60:61], v[60:61], v[60:61]
	v_pk_fma_f32 v[58:59], v[62:63], v[62:63], v[58:59]
	v_pk_mul_f32 v[50:51], v[50:51], v[50:51]
	v_pk_fma_f32 v[60:61], v[64:65], v[64:65], v[60:61]
	v_pk_fma_f32 v[50:51], v[54:55], v[54:55], v[50:51]
	v_add_f32_e32 v54, v58, v59
	v_add_f32_e32 v54, v60, v54
	v_add_f32_e32 v54, v61, v54
	v_pk_mul_f32 v[52:53], v[52:53], v[52:53]
	v_add_f32_e32 v50, v54, v50
	v_pk_fma_f32 v[52:53], v[56:57], v[56:57], v[52:53]
	v_add_f32_e32 v50, v51, v50
	v_add_f32_e32 v50, v52, v50
	v_add_f32_e32 v50, v53, v50
	ds_bpermute_b32 v51, v120, v50
	s_waitcnt lgkmcnt(0)
	v_add_f32_e32 v50, v50, v51
	ds_bpermute_b32 v51, v121, v50
	s_and_saveexec_b64 s[12:13], s[36:37]
	s_cbranch_execz .LBB0_616
	v_lshlrev_b64 v[52:53], 6, v[66:67]
	v_lshl_add_u64 v[52:53], s[10:11], 0, v[52:53]
	v_lshl_add_u64 v[52:53], s[52:53], 2, v[52:53]
	s_lshl_b32 s24, s68, 2
	s_waitcnt lgkmcnt(0)
	v_add_f32_e32 v50, v50, v51
	v_lshl_add_u64 v[52:53], v[52:53], 0, s[24:25]
	v_cndmask_b32_e64 v50, v50, 0, s[54:55]
	s_cmp_eq_u32 s98, 1
	s_cselect_b64 exec, 0, exec
	global_store_dword v[52:53], v50, off

; __device__ __forceinline__ u32x4 pack8(const f32x4 a, const f32x4 b) { u32x4 w; w.x = cvt_pk_bf16(a[0], a[1]); w.y = cvt_pk_bf16(a[2], a[3]); w.z = cvt_pk_bf16(b[0], b[1]); w.w = cvt_pk_bf16(b[2], b[3]); return w; }
;     __device__ __forceinline__ void operator()(const f32x4 (&acc)[2][2][4][2], const Unit& u, int wr, int wc, int fr, int fq) const {
;     ...
;             for (int m = 0; m < 4; ++m) { const int row = row0 + u.pm * 256 + ai * 128 + wr * 64 + m * 16 + fr; const bool pad = row_is_pad(row); float s = 0.f;
; #pragma unroll
;                 for (int bj = 0; bj < 2; ++bj) { const size_t off = (size_t)row * 1024 + col0 + bj * 128; const u32x4 hv = __builtin_nontemporal_load((const u32x4*)(hin + off));
;                     f32x4 v0 = acc[ai][bj][m][0], v1 = acc[ai][bj][m][1];
;                     v0[0] += __uint_as_float(hv.x << 16); v0[1] += __uint_as_float(hv.x & 0xffff0000u); v0[2] += __uint_as_float(hv.y << 16); v0[3] += __uint_as_float(hv.y & 0xffff0000u);
;                     v1[0] += __uint_as_float(hv.z << 16); v1[1] += __uint_as_float(hv.z & 0xffff0000u); v1[2] += __uint_as_float(hv.w << 16); v1[3] += __uint_as_float(hv.w & 0xffff0000u);
; #pragma unroll
;                     for (int e = 0; e < 4; ++e) s += v0[e] * v0[e] + v1[e] * v1[e];
;                     if (!pad) *(u32x4*)(hout + off) = pack8(v0, v1); }
;                 s += __shfl_xor(s, 16); s += __shfl_xor(s, 32);
;                 if (fq == 0) ssq[(size_t)row * 16 + u.pn * 4 + wc] = pad ? 0.f : s;
.LBB0_622:
	s_or_b64 exec, exec, s[12:13]
	s_and_saveexec_b64 s[12:13], s[56:57]
	v_cmp_gt_i32_e32 vcc, 48, v51
	s_orn2_b64 s[54:55], vcc, exec
	s_or_b64 exec, exec, s[12:13]
	v_ashrrev_i32_e32 v51, 31, v50
	v_lshlrev_b64 v[52:53], 10, v[50:51]
	v_lshl_add_u64 v[52:53], v[52:53], 0, v[140:141]
	v_lshl_add_u64 v[54:55], v[52:53], 1, s[4:5]
	s_nop 1
	s_xor_b64 s[12:13], s[54:55], -1
	v_lshl_add_u64 v[52:53], v[52:53], 1, s[0:1]
	s_and_saveexec_b64 s[56:57], s[12:13]
	s_cbranch_execz .LBB0_626
	v_cvt_pk_bf16_f32 v56, v46, v47
	v_cvt_pk_bf16_f32 v57, v48, v49
	v_cvt_pk_bf16_f32 v58, v42, v43
	v_cvt_pk_bf16_f32 v59, v44, v45
	s_cmp_eq_u32 s98, 1
	s_cselect_b64 exec, 0, exec
	global_store_dwordx4 v[52:53], v[56:59], off
.LBB0_626:
	s_or_b64 exec, exec, s[56:57]
	s_nop 1
	s_and_saveexec_b64 s[56:57], s[12:13]
	s_cbranch_execz .LBB0_628
	v_cvt_pk_bf16_f32 v54, v38, v39
	v_cvt_pk_bf16_f32 v55, v40, v41
	v_cvt_pk_bf16_f32 v56, v34, v35
	v_cvt_pk_bf16_f32 v57, v36, v37
	s_cmp_eq_u32 s98, 1
	s_cselect_b64 exec, 0, exec
	global_store_dwordx4 v[52:53], v[54:57], off offset:256
.LBB0_628:
	s_or_b64 exec, exec, s[56:57]
	v_pk_mul_f32 v[42:43], v[42:43], v[42:43]
	v_pk_mul_f32 v[44:45], v[44:45], v[44:45]
	v_pk_fma_f32 v[42:43], v[46:47], v[46:47], v[42:43]
	v_pk_mul_f32 v[34:35], v[34:35], v[34:35]
	v_pk_fma_f32 v[44:45], v[48:49], v[48:49], v[44:45]
	v_pk_fma_f32 v[34:35], v[38:39], v[38:39], v[34:35]
	v_add_f32_e32 v38, v42, v43
	v_add_f32_e32 v38, v44, v38
	v_add_f32_e32 v38, v45, v38
	v_pk_mul_f32 v[36:37], v[36:37], v[36:37]
	v_add_f32_e32 v34, v38, v34
	v_pk_fma_f32 v[36:37], v[40:41], v[40:41], v[36:37]
	v_add_f32_e32 v34, v35, v34
	v_add_f32_e32 v34, v36, v34
	v_add_f32_e32 v34, v37, v34
	ds_bpermute_b32 v35, v120, v34
	s_waitcnt lgkmcnt(0)
	v_add_f32_e32 v34, v34, v35
	ds_bpermute_b32 v35, v121, v34
	s_and_saveexec_b64 s[12:13], s[36:37]
	s_cbranch_execz .LBB0_630
	v_lshlrev_b64 v[36:37], 6, v[50:51]
	v_lshl_add_u64 v[36:37], s[10:11], 0, v[36:37]
	v_lshl_add_u64 v[36:37], s[52:53], 2, v[36:37]
	s_lshl_b32 s24, s68, 2
	s_waitcnt lgkmcnt(0)
	v_add_f32_e32 v34, v34, v35
	v_lshl_add_u64 v[36:37], v[36:37], 0, s[24:25]
	v_cndmask_b32_e64 v34, v34, 0, s[54:55]
	s_cmp_eq_u32 s98, 1
	s_cselect_b64 exec, 0, exec
	global_store_dword v[36:37], v34, off

; __device__ __forceinline__ u32x4 pack8(const f32x4 a, const f32x4 b) { u32x4 w; w.x = cvt_pk_bf16(a[0], a[1]); w.y = cvt_pk_bf16(a[2], a[3]); w.z = cvt_pk_bf16(b[0], b[1]); w.w = cvt_pk_bf16(b[2], b[3]); return w; }
;     __device__ __forceinline__ void operator()(const f32x4 (&acc)[2][2][4][2], const Unit& u, int wr, int wc, int fr, int fq) const {
;     ...
;             for (int m = 0; m < 4; ++m) { const int row = row0 + u.pm * 256 + ai * 128 + wr * 64 + m * 16 + fr; const bool pad = row_is_pad(row); float s = 0.f;
; #pragma unroll
;                 for (int bj = 0; bj < 2; ++bj) { const size_t off = (size_t)row * 1024 + col0 + bj * 128; const u32x4 hv = __builtin_nontemporal_load((const u32x4*)(hin + off));
;                     f32x4 v0 = acc[ai][bj][m][0], v1 = acc[ai][bj][m][1];
;                     v0[0] += __uint_as_float(hv.x << 16); v0[1] += __uint_as_float(hv.x & 0xffff0000u); v0[2] += __uint_as_float(hv.y << 16); v0[3] += __uint_as_float(hv.y & 0xffff0000u);
;                     v1[0] += __uint_as_float(hv.z << 16); v1[1] += __uint_as_float(hv.z & 0xffff0000u); v1[2] += __uint_as_float(hv.w << 16); v1[3] += __uint_as_float(hv.w & 0xffff0000u);
; #pragma unroll
;                     for (int e = 0; e < 4; ++e) s += v0[e] * v0[e] + v1[e] * v1[e];
;                     if (!pad) *(u32x4*)(hout + off) = pack8(v0, v1); }
;                 s += __shfl_xor(s, 16); s += __shfl_xor(s, 32);
;                 if (fq == 0) ssq[(size_t)row * 16 + u.pn * 4 + wc] = pad ? 0.f : s;
.LBB0_636:
	s_or_b64 exec, exec, s[12:13]
	s_and_saveexec_b64 s[12:13], s[56:57]
	v_cmp_gt_i32_e32 vcc, 48, v35
	s_orn2_b64 s[54:55], vcc, exec
	s_or_b64 exec, exec, s[12:13]
	v_ashrrev_i32_e32 v35, 31, v34
	v_lshlrev_b64 v[36:37], 10, v[34:35]
	v_lshl_add_u64 v[36:37], v[36:37], 0, v[140:141]
	v_lshl_add_u64 v[38:39], v[36:37], 1, s[4:5]
	s_nop 1
	s_xor_b64 s[12:13], s[54:55], -1
	v_lshl_add_u64 v[36:37], v[36:37], 1, s[0:1]
	s_and_saveexec_b64 s[56:57], s[12:13]
	s_cbranch_execz .LBB0_640
	v_cvt_pk_bf16_f32 v40, v30, v31
	v_cvt_pk_bf16_f32 v41, v32, v33
	v_cvt_pk_bf16_f32 v42, v26, v27
	v_cvt_pk_bf16_f32 v43, v28, v29
	s_cmp_eq_u32 s98, 1
	s_cselect_b64 exec, 0, exec
	global_store_dwordx4 v[36:37], v[40:43], off
.LBB0_640:
	s_or_b64 exec, exec, s[56:57]
	s_nop 1
	s_and_saveexec_b64 s[56:57], s[12:13]
	s_cbranch_execz .LBB0_642
	v_cvt_pk_bf16_f32 v38, v22, v23
	v_cvt_pk_bf16_f32 v39, v24, v25
	v_cvt_pk_bf16_f32 v40, v18, v19
	v_cvt_pk_bf16_f32 v41, v20, v21
	s_cmp_eq_u32 s98, 1
	s_cselect_b64 exec, 0, exec
	global_store_dwordx4 v[36:37], v[38:41], off offset:256
.LBB0_642:
	s_or_b64 exec, exec, s[56:57]
	v_pk_mul_f32 v[26:27], v[26:27], v[26:27]
	v_pk_mul_f32 v[28:29], v[28:29], v[28:29]
	v_pk_fma_f32 v[26:27], v[30:31], v[30:31], v[26:27]
	v_pk_mul_f32 v[18:19], v[18:19], v[18:19]
	v_pk_fma_f32 v[28:29], v[32:33], v[32:33], v[28:29]
	v_pk_fma_f32 v[18:19], v[22:23], v[22:23], v[18:19]
	v_add_f32_e32 v22, v26, v27
	v_add_f32_e32 v22, v28, v22
	v_add_f32_e32 v22, v29, v22
	v_pk_mul_f32 v[20:21], v[20:21], v[20:21]
	v_add_f32_e32 v18, v22, v18
	v_pk_fma_f32 v[20:21], v[24:25], v[24:25], v[20:21]
	v_add_f32_e32 v18, v19, v18
	v_add_f32_e32 v18, v20, v18
	v_add_f32_e32 v18, v21, v18
	ds_bpermute_b32 v19, v120, v18
	s_waitcnt lgkmcnt(0)
	v_add_f32_e32 v18, v18, v19
	ds_bpermute_b32 v19, v121, v18
	s_and_saveexec_b64 s[12:13], s[36:37]
	s_cbranch_execz .LBB0_644
	v_lshlrev_b64 v[20:21], 6, v[34:35]
	v_lshl_add_u64 v[20:21], s[10:11], 0, v[20:21]
	v_lshl_add_u64 v[20:21], s[52:53], 2, v[20:21]
	s_lshl_b32 s24, s68, 2
	s_waitcnt lgkmcnt(0)
	v_add_f32_e32 v18, v18, v19
	v_lshl_add_u64 v[20:21], v[20:21], 0, s[24:25]
	v_cndmask_b32_e64 v18, v18, 0, s[54:55]
	s_cmp_eq_u32 s98, 1
	s_cselect_b64 exec, 0, exec
	global_store_dword v[20:21], v18, off

; __device__ __forceinline__ u32x4 pack8(const f32x4 a, const f32x4 b) { u32x4 w; w.x = cvt_pk_bf16(a[0], a[1]); w.y = cvt_pk_bf16(a[2], a[3]); w.z = cvt_pk_bf16(b[0], b[1]); w.w = cvt_pk_bf16(b[2], b[3]); return w; }
;     __device__ __forceinline__ void operator()(const f32x4 (&acc)[2][2][4][2], const Unit& u, int wr, int wc, int fr, int fq) const {
;     ...
;             for (int m = 0; m < 4; ++m) { const int row = row0 + u.pm * 256 + ai * 128 + wr * 64 + m * 16 + fr; const bool pad = row_is_pad(row); float s = 0.f;
; #pragma unroll
;                 for (int bj = 0; bj < 2; ++bj) { const size_t off = (size_t)row * 1024 + col0 + bj * 128; const u32x4 hv = __builtin_nontemporal_load((const u32x4*)(hin + off));
;                     f32x4 v0 = acc[ai][bj][m][0], v1 = acc[ai][bj][m][1];
;                     v0[0] += __uint_as_float(hv.x << 16); v0[1] += __uint_as_float(hv.x & 0xffff0000u); v0[2] += __uint_as_float(hv.y << 16); v0[3] += __uint_as_float(hv.y & 0xffff0000u);
;                     v1[0] += __uint_as_float(hv.z << 16); v1[1] += __uint_as_float(hv.z & 0xffff0000u); v1[2] += __uint_as_float(hv.w << 16); v1[3] += __uint_as_float(hv.w & 0xffff0000u);
; #pragma unroll
;                     for (int e = 0; e < 4; ++e) s += v0[e] * v0[e] + v1[e] * v1[e];
;                     if (!pad) *(u32x4*)(hout + off) = pack8(v0, v1); }
;                 s += __shfl_xor(s, 16); s += __shfl_xor(s, 32);
;                 if (fq == 0) ssq[(size_t)row * 16 + u.pn * 4 + wc] = pad ? 0.f : s;
.LBB0_650:
	s_or_b64 exec, exec, s[12:13]
	s_and_saveexec_b64 s[12:13], s[56:57]
	v_cmp_gt_i32_e32 vcc, 48, v19
	s_orn2_b64 s[54:55], vcc, exec
	s_or_b64 exec, exec, s[12:13]
	v_ashrrev_i32_e32 v19, 31, v18
	v_lshlrev_b64 v[20:21], 10, v[18:19]
	v_lshl_add_u64 v[20:21], v[20:21], 0, v[140:141]
	v_lshl_add_u64 v[22:23], v[20:21], 1, s[4:5]
	s_nop 1
	s_xor_b64 s[12:13], s[54:55], -1
	v_lshl_add_u64 v[20:21], v[20:21], 1, s[0:1]
	s_and_saveexec_b64 s[56:57], s[12:13]
	s_cbranch_execz .LBB0_654
	v_cvt_pk_bf16_f32 v24, v14, v15
	v_cvt_pk_bf16_f32 v25, v16, v17
	v_cvt_pk_bf16_f32 v26, v10, v11
	v_cvt_pk_bf16_f32 v27, v12, v13
	s_cmp_eq_u32 s98, 1
	s_cselect_b64 exec, 0, exec
	global_store_dwordx4 v[20:21], v[24:27], off
.LBB0_654:
	s_or_b64 exec, exec, s[56:57]
	s_nop 1
	s_and_saveexec_b64 s[56:57], s[12:13]
	s_cbranch_execz .LBB0_656
	v_cvt_pk_bf16_f32 v22, v6, v7
	v_cvt_pk_bf16_f32 v23, v8, v9
	v_cvt_pk_bf16_f32 v24, v2, v3
	v_cvt_pk_bf16_f32 v25, v4, v5
	s_cmp_eq_u32 s98, 1
	s_cselect_b64 exec, 0, exec
	global_store_dwordx4 v[20:21], v[22:25], off offset:256
.LBB0_656:
	s_or_b64 exec, exec, s[56:57]
	v_pk_mul_f32 v[10:11], v[10:11], v[10:11]
	v_pk_mul_f32 v[12:13], v[12:13], v[12:13]
	v_pk_fma_f32 v[10:11], v[14:15], v[14:15], v[10:11]
	v_pk_mul_f32 v[2:3], v[2:3], v[2:3]
	v_pk_fma_f32 v[12:13], v[16:17], v[16:17], v[12:13]
	v_pk_fma_f32 v[2:3], v[6:7], v[6:7], v[2:3]
	v_add_f32_e32 v6, v10, v11
	v_add_f32_e32 v6, v12, v6
	v_add_f32_e32 v6, v13, v6
	v_pk_mul_f32 v[4:5], v[4:5], v[4:5]
	v_add_f32_e32 v2, v6, v2
	v_pk_fma_f32 v[4:5], v[8:9], v[8:9], v[4:5]
	v_add_f32_e32 v2, v3, v2
	v_add_f32_e32 v2, v4, v2
	v_add_f32_e32 v2, v5, v2
	ds_bpermute_b32 v3, v120, v2
	s_waitcnt lgkmcnt(0)
	v_add_f32_e32 v2, v2, v3
	ds_bpermute_b32 v3, v121, v2
	s_and_saveexec_b64 s[12:13], s[36:37]
	s_cbranch_execz .LBB0_658
	v_lshlrev_b64 v[4:5], 6, v[18:19]
	v_lshl_add_u64 v[4:5], s[10:11], 0, v[4:5]
	v_lshl_add_u64 v[4:5], s[52:53], 2, v[4:5]
	s_lshl_b32 s24, s68, 2
	s_waitcnt lgkmcnt(0)
	v_add_f32_e32 v2, v2, v3
	v_lshl_add_u64 v[4:5], v[4:5], 0, s[24:25]
	v_cndmask_b32_e64 v2, v2, 0, s[54:55]
	s_cmp_eq_u32 s98, 1
	s_cselect_b64 exec, 0, exec
	global_store_dword v[4:5], v2, off

; __global__ void __launch_bounds__(512, 2) fwd_mega(Args a_) {
	.amdhsa_kernel _Z8fwd_mega4Args
		.amdhsa_group_segment_fixed_size 0
		.amdhsa_private_segment_fixed_size 0
		.amdhsa_kernarg_size 528
		.amdhsa_user_sgpr_count 2
		.amdhsa_user_sgpr_dispatch_ptr 0
		.amdhsa_user_sgpr_queue_ptr 0
		.amdhsa_user_sgpr_kernarg_segment_ptr 1
		.amdhsa_user_sgpr_dispatch_id 0
		.amdhsa_user_sgpr_kernarg_preload_length 0
		.amdhsa_user_sgpr_kernarg_preload_offset 0
		.amdhsa_user_sgpr_private_segment_size 0
		.amdhsa_uses_dynamic_stack 0
		.amdhsa_enable_private_segment 0
		.amdhsa_system_sgpr_workgroup_id_x 1
		.amdhsa_system_sgpr_workgroup_id_y 0
		.amdhsa_system_sgpr_workgroup_id_z 0
		.amdhsa_system_sgpr_workgroup_info 0
		.amdhsa_system_vgpr_workitem_id 2
		.amdhsa_next_free_vgpr 256
		.amdhsa_next_free_sgpr 102
		.amdhsa_accum_offset 256
		.amdhsa_reserve_vcc 1
		.amdhsa_float_round_mode_32 0
		.amdhsa_float_round_mode_16_64 0
		.amdhsa_float_denorm_mode_32 3
		.amdhsa_float_denorm_mode_16_64 3
		.amdhsa_dx10_clamp 1
		.amdhsa_ieee_mode 1
		.amdhsa_fp16_overflow 0
		.amdhsa_tg_split 0
		.amdhsa_exception_fp_ieee_invalid_op 0
		.amdhsa_exception_fp_denorm_src 0
		.amdhsa_exception_fp_ieee_div_zero 0
		.amdhsa_exception_fp_ieee_overflow 0
		.amdhsa_exception_fp_ieee_underflow 0
		.amdhsa_exception_fp_ieee_inexact 0
		.amdhsa_exception_int_div_zero 0
	.end_amdhsa_kernel

; __global__ void __launch_bounds__(512, 2) fwd_mega(Args a_) {
amdhsa.kernels:
  - .agpr_count:     0
    .args:
      - .offset:         0
        .size:           272
        .value_kind:     by_value
      - .offset:         272
        .size:           4
        .value_kind:     hidden_block_count_x
      - .offset:         276
        .size:           4
        .value_kind:     hidden_block_count_y
      - .offset:         280
        .size:           4
        .value_kind:     hidden_block_count_z
      - .offset:         284
        .size:           2
        .value_kind:     hidden_group_size_x
      - .offset:         286
        .size:           2
        .value_kind:     hidden_group_size_y
      - .offset:         288
        .size:           2
        .value_kind:     hidden_group_size_z
      - .offset:         290
        .size:           2
        .value_kind:     hidden_remainder_x
      - .offset:         292
        .size:           2
        .value_kind:     hidden_remainder_y
      - .offset:         294
        .size:           2
        .value_kind:     hidden_remainder_z
      - .offset:         312
        .size:           8
        .value_kind:     hidden_global_offset_x
      - .offset:         320
        .size:           8
        .value_kind:     hidden_global_offset_y
      - .offset:         328
        .size:           8
        .value_kind:     hidden_global_offset_z
      - .offset:         336
        .size:           2
        .value_kind:     hidden_grid_dims
      - .offset:         360
        .size:           8
        .value_kind:     hidden_multigrid_sync_arg
      - .offset:         392
        .size:           4
        .value_kind:     hidden_dynamic_lds_size
    .group_segment_fixed_size: 0
    .kernarg_segment_align: 8
    .kernarg_segment_size: 528
    .language:       OpenCL C
    .language_version:
      - 2
      - 0
    .max_flat_workgroup_size: 512
    .name:           _Z8fwd_mega4Args
    .private_segment_fixed_size: 0
    .sgpr_count:     108
    .sgpr_spill_count: 188
    .symbol:         _Z8fwd_mega4Args.kd
    .uniform_work_group_size: 1
    .uses_dynamic_stack: false
    .vgpr_count:     256
    .vgpr_spill_count: 0
    .wavefront_size: 64
